# RG-LRU pass-2 carry-in: the up-to-7 earlier-segment maps loaded in one batch instead of one dependent round trip each (on top of write-through stores, no wbl2)
# speedup vs baseline: 1.0360x; 1.0015x over previous
.LBB0_768:
	global_load_dwordx2 v[6:7], v[4:5], off
	global_load_dwordx2 v[8:9], v[4:5], off offset:512
	global_load_dwordx2 v[10:11], v[4:5], off offset:1024
	global_load_dwordx2 v[12:13], v[4:5], off offset:1536
	global_load_dwordx2 v[14:15], v[4:5], off offset:2048
	global_load_dwordx2 v[16:17], v[4:5], off offset:2560
	global_load_dwordx2 v[18:19], v[4:5], off offset:3072
	s_waitcnt vmcnt(0)
	v_fma_f32 v2, v2, v6, v7
	s_cmp_lt_u32 s20, 2
	s_cbranch_scc1 .LBB0_770
	v_fma_f32 v2, v2, v8, v9
	s_cmp_lt_u32 s20, 3
	s_cbranch_scc1 .LBB0_770
	v_fma_f32 v2, v2, v10, v11
	s_cmp_lt_u32 s20, 4
	s_cbranch_scc1 .LBB0_770
	v_fma_f32 v2, v2, v12, v13
	s_cmp_lt_u32 s20, 5
	s_cbranch_scc1 .LBB0_770
	v_fma_f32 v2, v2, v14, v15
	s_cmp_lt_u32 s20, 6
	s_cbranch_scc1 .LBB0_770
	v_fma_f32 v2, v2, v16, v17
	s_cmp_lt_u32 s20, 7
	s_cbranch_scc1 .LBB0_770
	v_fma_f32 v2, v2, v18, v19
	s_branch .LBB0_770
